# F1 + every workgroup starts an L2 write-back when it arrives at a grid barrier
# baseline (speedup 1.0000x reference)
.LBB1_162:
	v_readlane_b32 s1, v255, 43
	s_add_i32 s1, s1, 2
	s_cmp_ge_i32 s1, s77
	s_cbranch_scc1 .LBB1_212
	s_waitcnt vmcnt(0)
	s_barrier
	s_mov_b64 s[2:3], exec
	v_readlane_b32 s6, v255, 20
	v_readlane_b32 s7, v255, 21
	s_and_b64 s[6:7], s[2:3], s[6:7]
	s_mov_b64 exec, s[6:7]
	s_cbranch_execz .LBB1_211
	v_readlane_b32 s5, v255, 18
	s_waitcnt vmcnt(0) expcnt(0) lgkmcnt(0)
	buffer_wbl2 sc1
	s_nop 0
	v_mov_b32_e32 v0, s5
	ds_read_b32 v2, v0
	v_readlane_b32 s5, v255, 19
	s_waitcnt lgkmcnt(0)
	v_cmp_ne_u32_e32 vcc, 0, v2
	v_mov_b32_e32 v0, s5
	ds_read_b32 v0, v0
	s_cbranch_vccnz .LBB1_179
	v_readlane_b32 s10, v253, 8
	v_readlane_b32 s11, v253, 9
	s_load_dwordx2 s[6:7], s[10:11], 0x4
	s_waitcnt lgkmcnt(0)
	s_mul_i32 s5, s6, s33
	s_mul_i32 s5, s5, s7
	s_mov_b32 s6, 1
	s_branch .LBB1_167

.LBB1_295:
	v_readlane_b32 s1, v255, 43
	s_add_i32 s1, s1, 3
	s_cmp_lt_i32 s1, s77
	s_cselect_b64 s[16:17], -1, 0
	s_and_b64 s[2:3], s[2:3], s[16:17]
	s_andn2_b64 vcc, exec, s[2:3]
	s_cbranch_vccnz .LBB1_345
	s_waitcnt vmcnt(0)
	s_waitcnt vmcnt(0)
	s_barrier
	s_mov_b64 s[2:3], exec
	v_readlane_b32 s6, v255, 20
	v_readlane_b32 s7, v255, 21
	s_and_b64 s[6:7], s[2:3], s[6:7]
	s_mov_b64 exec, s[6:7]
	s_cbranch_execz .LBB1_344
	v_readlane_b32 s5, v255, 18
	s_waitcnt vmcnt(0) expcnt(0) lgkmcnt(0)
	buffer_wbl2 sc1
	s_nop 0
	v_mov_b32_e32 v0, s5
	ds_read_b32 v2, v0
	v_readlane_b32 s5, v255, 19
	s_waitcnt lgkmcnt(0)
	v_cmp_ne_u32_e32 vcc, 0, v2
	v_mov_b32_e32 v0, s5
	ds_read_b32 v0, v0
	s_cbranch_vccnz .LBB1_312
	v_readlane_b32 s10, v253, 8
	v_readlane_b32 s11, v253, 9
	s_load_dwordx2 s[6:7], s[10:11], 0x4
	s_waitcnt lgkmcnt(0)
	s_mul_i32 s5, s6, s33
	s_mul_i32 s5, s5, s7
	s_mov_b32 s6, 1
	s_branch .LBB1_300

.LBB1_418:
	v_readlane_b32 s1, v255, 43
	s_add_i32 s1, s1, 4
	s_cmp_ge_i32 s1, s77
	s_cbranch_scc1 .LBB1_468
	s_waitcnt vmcnt(0)
	s_waitcnt vmcnt(0)
	s_barrier
	s_mov_b64 s[2:3], exec
	v_readlane_b32 s6, v255, 20
	v_readlane_b32 s7, v255, 21
	s_and_b64 s[6:7], s[2:3], s[6:7]
	s_mov_b64 exec, s[6:7]
	s_cbranch_execz .LBB1_467
	v_readlane_b32 s5, v255, 18
	s_waitcnt vmcnt(0) expcnt(0) lgkmcnt(0)
	buffer_wbl2 sc1
	s_nop 0
	v_mov_b32_e32 v0, s5
	ds_read_b32 v2, v0
	v_readlane_b32 s5, v255, 19
	s_waitcnt lgkmcnt(0)
	v_cmp_ne_u32_e32 vcc, 0, v2
	v_mov_b32_e32 v0, s5
	ds_read_b32 v0, v0
	s_cbranch_vccnz .LBB1_435
	v_readlane_b32 s10, v253, 8
	v_readlane_b32 s11, v253, 9
	s_load_dwordx2 s[6:7], s[10:11], 0x4
	s_waitcnt lgkmcnt(0)
	s_mul_i32 s5, s6, s33
	s_mul_i32 s5, s5, s7
	s_mov_b32 s6, 1
	s_branch .LBB1_423

.LBB1_553:
	v_readlane_b32 s1, v255, 43
	s_add_i32 s1, s1, 5
	s_cmp_ge_i32 s1, s77
	s_cbranch_scc1 .LBB1_603
	s_waitcnt vmcnt(0)
	s_waitcnt vmcnt(0)
	s_barrier
	s_mov_b64 s[2:3], exec
	v_readlane_b32 s6, v255, 20
	v_readlane_b32 s7, v255, 21
	s_and_b64 s[6:7], s[2:3], s[6:7]
	s_mov_b64 exec, s[6:7]
	s_cbranch_execz .LBB1_602
	v_readlane_b32 s5, v255, 18
	s_waitcnt vmcnt(0) expcnt(0) lgkmcnt(0)
	buffer_wbl2 sc1
	s_nop 0
	v_mov_b32_e32 v0, s5
	ds_read_b32 v2, v0
	v_readlane_b32 s5, v255, 19
	s_waitcnt lgkmcnt(0)
	v_cmp_ne_u32_e32 vcc, 0, v2
	v_mov_b32_e32 v0, s5
	ds_read_b32 v0, v0
	s_cbranch_vccnz .LBB1_570
	v_readlane_b32 s10, v253, 8
	v_readlane_b32 s11, v253, 9
	s_load_dwordx2 s[6:7], s[10:11], 0x4
	s_waitcnt lgkmcnt(0)
	s_mul_i32 s5, s6, s33
	s_mul_i32 s5, s5, s7
	s_mov_b32 s6, 1
	s_branch .LBB1_558

.LBB1_651:
	v_readlane_b32 s1, v255, 43
	s_add_i32 s1, s1, 6
	s_cmp_lt_i32 s1, s77
	s_cselect_b64 s[16:17], -1, 0
	s_and_b64 s[2:3], s[42:43], s[16:17]
	s_andn2_b64 vcc, exec, s[2:3]
	s_cbranch_vccnz .LBB1_701
	s_waitcnt vmcnt(0)
	s_waitcnt vmcnt(0)
	s_barrier
	s_mov_b64 s[2:3], exec
	v_readlane_b32 s6, v255, 20
	v_readlane_b32 s7, v255, 21
	s_and_b64 s[6:7], s[2:3], s[6:7]
	s_mov_b64 exec, s[6:7]
	s_cbranch_execz .LBB1_700
	v_readlane_b32 s5, v255, 18
	s_waitcnt vmcnt(0) expcnt(0) lgkmcnt(0)
	buffer_wbl2 sc1
	s_nop 0
	v_mov_b32_e32 v0, s5
	ds_read_b32 v2, v0
	v_readlane_b32 s5, v255, 19
	s_waitcnt lgkmcnt(0)
	v_cmp_ne_u32_e32 vcc, 0, v2
	v_mov_b32_e32 v0, s5
	ds_read_b32 v0, v0
	s_cbranch_vccnz .LBB1_668
	v_readlane_b32 s10, v253, 8
	v_readlane_b32 s11, v253, 9
	s_load_dwordx2 s[6:7], s[10:11], 0x4
	s_waitcnt lgkmcnt(0)
	s_mul_i32 s5, s6, s33
	s_mul_i32 s5, s5, s7
	s_mov_b32 s6, 1
	s_branch .LBB1_656

.LBB1_815:
	v_readlane_b32 s1, v255, 43
	s_add_i32 s1, s1, 7
	s_cmp_lt_i32 s1, s77
	s_cselect_b64 s[16:17], -1, 0
	s_and_b64 s[2:3], s[2:3], s[16:17]
	s_andn2_b64 vcc, exec, s[2:3]
	s_cbranch_vccnz .LBB1_865
	s_waitcnt vmcnt(0)
	s_waitcnt vmcnt(0)
	s_barrier
	s_mov_b64 s[2:3], exec
	v_readlane_b32 s6, v255, 20
	v_readlane_b32 s7, v255, 21
	s_and_b64 s[6:7], s[2:3], s[6:7]
	s_mov_b64 exec, s[6:7]
	s_cbranch_execz .LBB1_864
	v_readlane_b32 s5, v255, 18
	s_waitcnt vmcnt(0) expcnt(0) lgkmcnt(0)
	buffer_wbl2 sc1
	s_nop 0
	v_mov_b32_e32 v0, s5
	ds_read_b32 v2, v0
	v_readlane_b32 s5, v255, 19
	s_waitcnt lgkmcnt(0)
	v_cmp_ne_u32_e32 vcc, 0, v2
	v_mov_b32_e32 v0, s5
	ds_read_b32 v0, v0
	s_cbranch_vccnz .LBB1_832
	v_readlane_b32 s10, v253, 8
	v_readlane_b32 s11, v253, 9
	s_load_dwordx2 s[6:7], s[10:11], 0x4
	s_waitcnt lgkmcnt(0)
	s_mul_i32 s5, s6, s33
	s_mul_i32 s5, s5, s7
	s_mov_b32 s6, 1
	s_branch .LBB1_820

.LBB1_873:
	v_readlane_b32 s1, v255, 43
	s_add_i32 s1, s1, 8
	s_cmp_ge_i32 s1, s77
	s_cbranch_scc1 .LBB1_885
	s_waitcnt vmcnt(0)
	s_waitcnt vmcnt(0)
	s_barrier
	s_mov_b64 s[2:3], exec
	v_readlane_b32 s6, v255, 20
	v_readlane_b32 s7, v255, 21
	s_and_b64 s[6:7], s[2:3], s[6:7]
	s_movk_i32 s25, 0x120
	s_mov_b64 exec, s[6:7]
	s_cbranch_execz .LBB1_923
	v_readlane_b32 s5, v255, 18
	s_waitcnt vmcnt(0) expcnt(0) lgkmcnt(0)
	buffer_wbl2 sc1
	s_nop 0
	v_mov_b32_e32 v0, s5
	ds_read_b32 v2, v0
	v_readlane_b32 s5, v255, 19
	s_waitcnt lgkmcnt(0)
	v_cmp_ne_u32_e32 vcc, 0, v2
	v_mov_b32_e32 v0, s5
	ds_read_b32 v0, v0
	s_cbranch_vccnz .LBB1_891
	v_readlane_b32 s10, v253, 8
	v_readlane_b32 s11, v253, 9
	s_load_dwordx2 s[6:7], s[10:11], 0x4
	s_waitcnt lgkmcnt(0)
	s_mul_i32 s5, s6, s33
	s_mul_i32 s5, s5, s7
	s_mov_b32 s6, 1
	s_branch .LBB1_878

.LBB1_1126:
	v_readlane_b32 s56, v253, 42
	v_readlane_b32 s1, v255, 43
	v_readlane_b32 s57, v253, 43
	s_add_i32 s1, s1, 9
	s_mov_b64 s[76:77], s[56:57]
	s_cmp_lt_i32 s1, s77
	v_readlane_b32 s2, v255, 45
	s_cselect_b64 s[16:17], -1, 0
	v_readlane_b32 s3, v255, 46
	s_and_b64 s[2:3], s[2:3], s[16:17]
	s_andn2_b64 vcc, exec, s[2:3]
	v_readlane_b32 s58, v253, 44
	v_readlane_b32 s59, v253, 45
	s_cbranch_vccnz .LBB1_1176
	s_waitcnt vmcnt(0)
	s_waitcnt vmcnt(0) lgkmcnt(0)
	s_barrier
	s_mov_b64 s[2:3], exec
	v_readlane_b32 s6, v255, 20
	v_readlane_b32 s7, v255, 21
	s_and_b64 s[6:7], s[2:3], s[6:7]
	s_mov_b64 exec, s[6:7]
	s_cbranch_execz .LBB1_1175
	v_readlane_b32 s5, v255, 18
	s_waitcnt vmcnt(0) expcnt(0) lgkmcnt(0)
	buffer_wbl2 sc1
	s_nop 0
	v_mov_b32_e32 v0, s5
	ds_read_b32 v2, v0
	v_readlane_b32 s5, v255, 19
	s_waitcnt lgkmcnt(0)
	v_cmp_ne_u32_e32 vcc, 0, v2
	v_mov_b32_e32 v0, s5
	ds_read_b32 v0, v0
	s_cbranch_vccnz .LBB1_1143
	v_readlane_b32 s10, v253, 8
	v_readlane_b32 s11, v253, 9
	s_load_dwordx2 s[6:7], s[10:11], 0x4
	s_waitcnt lgkmcnt(0)
	s_mul_i32 s5, s6, s33
	s_mul_i32 s5, s5, s7
	s_mov_b32 s6, 1
	s_branch .LBB1_1131

.LBB1_1186:
	s_or_b64 exec, exec, s[2:3]
	v_readlane_b32 s1, v255, 43
	s_add_i32 s1, s1, 10
	s_cmp_ge_i32 s1, s77
	s_cbranch_scc1 .LBB1_1236
	s_waitcnt vmcnt(0)
	s_waitcnt vmcnt(0) lgkmcnt(0)
	s_barrier
	s_mov_b64 s[2:3], exec
	v_readlane_b32 s6, v255, 20
	v_readlane_b32 s7, v255, 21
	s_and_b64 s[6:7], s[2:3], s[6:7]
	s_mov_b64 exec, s[6:7]
	s_cbranch_execz .LBB1_1235
	v_readlane_b32 s5, v255, 18
	s_waitcnt vmcnt(0) expcnt(0) lgkmcnt(0)
	buffer_wbl2 sc1
	s_nop 0
	v_mov_b32_e32 v0, s5
	ds_read_b32 v2, v0
	v_readlane_b32 s5, v255, 19
	s_waitcnt lgkmcnt(0)
	v_cmp_ne_u32_e32 vcc, 0, v2
	v_mov_b32_e32 v0, s5
	ds_read_b32 v0, v0
	s_cbranch_vccnz .LBB1_1203
	v_readlane_b32 s10, v253, 8
	v_readlane_b32 s11, v253, 9
	s_load_dwordx2 s[6:7], s[10:11], 0x4
	s_waitcnt lgkmcnt(0)
	s_mul_i32 s5, s6, s33
	s_mul_i32 s5, s5, s7
	s_mov_b32 s6, 1
	s_branch .LBB1_1191

.LBB1_1270:
	v_readlane_b32 s1, v255, 18
	s_waitcnt vmcnt(0) expcnt(0) lgkmcnt(0)
	buffer_wbl2 sc1
	s_nop 0
	v_mov_b32_e32 v0, s1
	ds_read_b32 v2, v0
	v_readlane_b32 s1, v255, 19
	s_waitcnt lgkmcnt(0)
	v_cmp_ne_u32_e32 vcc, 0, v2
	v_mov_b32_e32 v0, s1
	ds_read_b32 v0, v0
	s_cbranch_vccnz .LBB1_1285
	v_readlane_b32 s10, v253, 8
	v_readlane_b32 s11, v253, 9
	s_load_dwordx2 s[6:7], s[10:11], 0x4
	s_mov_b32 s5, 1
	s_waitcnt lgkmcnt(0)
	s_mul_i32 s1, s6, s33
	s_mul_i32 s1, s1, s7
	s_branch .LBB1_1273
